# k17
# speedup vs baseline: 1.0340x; 1.0005x over previous
; #define MFMA32(a, b, c) __builtin_amdgcn_mfma_f32_32x32x16_bf16((a), (b), (c), 0, 0, 0)
; DI void attn_unit(unsigned char* smem, const Params& P, int bh, int qb) {
;     ...
;     if (more) {
;       const bf16_t* kp = kbuf + (size_t)(jt + 1) * 64 * 192;
;       kr0 = *(const uint4*)(kp + kgo + 0); kr1 = *(const uint4*)(kp + kgo + 32); kr2 = *(const uint4*)(kp + kgo + 64); kr3 = *(const uint4*)(kp + kgo + 96); kr4 = *(const uint4*)(kp + kgo + 128); kr5 = *(const uint4*)(kp + kgo + 160);
;     }
;     __builtin_amdgcn_sched_barrier(0);
;     f32x16 S[2];
;     const float sref = (jt == 0) ? 0.f : mrun;
;     if (active) {
; #pragma unroll
;       for (int a = 0; a < 2; ++a)
; #pragma unroll
;         for (int i = 0; i < 16; ++i) S[a][i] = -sref;
;       __builtin_amdgcn_s_setprio(1);
; #pragma unroll
;       for (int ks = 0; ks < 12; ++ks) {
;         const bf16x8 a0 = *(const bf16x8*)(cK + l31 * KLD + ks * 16 + hh * 8), a1 = *(const bf16x8*)(cK + (32 + l31) * KLD + ks * 16 + hh * 8);
;         S[0] = MFMA32(a0, qf[ks], S[0]); S[1] = MFMA32(a1, qf[ks], S[1]);
;       }
;     ...
;     if (active) {
;       __builtin_amdgcn_s_setprio(1);
; #pragma unroll
;       for (int kt = 0; kt < 2; ++kt)
; #pragma unroll
;         for (int s2 = 0; s2 < 2; ++s2) {
;           uint4 pp; pp.x = pk2(S[kt][8 * s2], S[kt][8 * s2 + 1]); pp.y = pk2(S[kt][8 * s2 + 2], S[kt][8 * s2 + 3]);
;           pp.z = pk2(S[kt][8 * s2 + 4], S[kt][8 * s2 + 5]); pp.w = pk2(S[kt][8 * s2 + 6], S[kt][8 * s2 + 7]);
;           const bf16x8 pb = __builtin_bit_cast(bf16x8, pp);
; #pragma unroll
;           for (int d = 0; d < 4; ++d) {
;             const bf16x8 vf = *(const bf16x8*)(sV + (d * 32 + l31) * LDK + kt * 32 + s2 * 16 + hh * 8);
;             O[d] = MFMA32(vf, pb, O[d]);
;           }
;         }
;       __builtin_amdgcn_s_setprio(0);
;     }
.LBB0_488:
	s_add_i32 s21, s19, 0x80
	s_bitcmp0_b32 s21, 0
	s_cselect_b64 s[14:15], -1, 0
	s_add_i32 s10, s20, 64
	v_cmp_le_i32_e64 s[2:3], s10, v220
	v_cmp_le_i32_e64 s[98:99], s20, v220
	s_cmp_lg_u64 s[2:3], 0
	s_cbranch_scc0 .Lslow_0
	s_and_b64 s[22:23], s[14:15], exec
	s_cselect_b32 s22, s9, s28
	v_add3_u32 v243, s22, v197, v201
	s_setprio 1
	ds_read_b128 v[180:183], v221 offset:25600
	ds_read_b128 v[184:187], v222 offset:25600
	ds_read_b128 v[226:229], v223 offset:25600
	ds_read_b128 v[230:233], v224 offset:25600
	ds_read_b128 v[244:247], v221 offset:25632
	ds_read_b128 v[248:251], v222 offset:25632
	ds_read_b128 v[252:255], v223 offset:25632
	v_cvt_pk_bf16_f32 v176, v36, v37
	v_cvt_pk_bf16_f32 v177, v38, v39
	v_cvt_pk_bf16_f32 v178, v40, v41
	v_cvt_pk_bf16_f32 v179, v42, v43
	v_cvt_pk_bf16_f32 v172, v44, v45
	v_cvt_pk_bf16_f32 v173, v46, v47
	v_cvt_pk_bf16_f32 v174, v48, v49
	v_cvt_pk_bf16_f32 v175, v50, v51
	s_waitcnt lgkmcnt(6)
	v_mfma_f32_32x32x16_bf16 v[84:99], v[180:183], v[176:179], v[84:99]
	ds_read_b128 v[180:183], v224 offset:25632
	global_load_dwordx4 v[148:151], v[202:203], off
	s_waitcnt lgkmcnt(6)
	v_mfma_f32_32x32x16_bf16 v[68:83], v[184:187], v[176:179], v[68:83]
	ds_read_b128 v[184:187], v221 offset:25664
	global_load_dwordx4 v[152:155], v[202:203], off offset:64
	s_waitcnt lgkmcnt(6)
	v_mfma_f32_32x32x16_bf16 v[52:67], v[226:229], v[176:179], v[52:67]
	ds_read_b128 v[226:229], v222 offset:25664
	global_load_dwordx4 v[156:159], v[202:203], off offset:128
	s_waitcnt lgkmcnt(6)
	v_mfma_f32_32x32x16_bf16 v[4:19], v[230:233], v[176:179], v[4:19]
	ds_read_b128 v[230:233], v223 offset:25664
	global_load_dwordx4 v[160:163], v[202:203], off offset:192
	s_waitcnt lgkmcnt(6)
	v_mfma_f32_32x32x16_bf16 v[84:99], v[244:247], v[172:175], v[84:99]
	ds_read_b128 v[244:247], v224 offset:25664
	global_load_dwordx4 v[164:167], v[202:203], off offset:256
	v_cvt_pk_bf16_f32 v176, v20, v21
	v_cvt_pk_bf16_f32 v177, v22, v23
	v_cvt_pk_bf16_f32 v178, v24, v25
	v_cvt_pk_bf16_f32 v179, v26, v27
	s_waitcnt lgkmcnt(6)
	v_mfma_f32_32x32x16_bf16 v[68:83], v[248:251], v[172:175], v[68:83]
	ds_read_b128 v[248:251], v221 offset:25696
	global_load_dwordx4 v[168:171], v[202:203], off offset:320
	s_waitcnt lgkmcnt(6)
	v_mfma_f32_32x32x16_bf16 v[52:67], v[252:255], v[172:175], v[52:67]
	ds_read_b128 v[252:255], v222 offset:25696
	s_waitcnt lgkmcnt(6)
	v_mfma_f32_32x32x16_bf16 v[4:19], v[180:183], v[172:175], v[4:19]
	ds_read_b128 v[180:183], v223 offset:25696
	s_waitcnt lgkmcnt(6)
	v_mfma_f32_32x32x16_bf16 v[84:99], v[184:187], v[176:179], v[84:99]
	ds_read_b128 v[184:187], v224 offset:25696
	v_cvt_pk_bf16_f32 v172, v28, v29
	v_cvt_pk_bf16_f32 v173, v30, v31
	v_cvt_pk_bf16_f32 v174, v32, v33
	v_cvt_pk_bf16_f32 v175, v34, v35
	s_waitcnt lgkmcnt(6)
	v_mfma_f32_32x32x16_bf16 v[68:83], v[226:229], v[176:179], v[68:83]
	v_xor_b32_e32 v20, 0x80000000, v200
	v_mov_b32_e32 v21, v20
	v_mov_b32_e32 v22, v20
	v_mov_b32_e32 v23, v20
	ds_read_b128 v[226:229], v243 offset:12832
	s_waitcnt lgkmcnt(6)
	v_mfma_f32_32x32x16_bf16 v[52:67], v[230:233], v[176:179], v[52:67]
	v_mov_b32_e32 v24, v20
	v_mov_b32_e32 v25, v20
	v_mov_b32_e32 v26, v20
	v_mov_b32_e32 v27, v20
	ds_read_b128 v[230:233], v243 offset:64
	s_waitcnt lgkmcnt(6)
	v_mfma_f32_32x32x16_bf16 v[4:19], v[244:247], v[176:179], v[4:19]
	v_mov_b32_e32 v28, v20
	v_mov_b32_e32 v29, v20
	v_mov_b32_e32 v30, v20
	v_mov_b32_e32 v31, v20
	ds_read_b128 v[244:247], v243
	s_waitcnt lgkmcnt(6)
	v_mfma_f32_32x32x16_bf16 v[84:99], v[248:251], v[172:175], v[84:99]
	v_mov_b32_e32 v32, v20
	v_mov_b32_e32 v33, v20
	v_mov_b32_e32 v34, v20
	v_mov_b32_e32 v35, v20
	ds_read_b128 v[248:251], v243 offset:12800
	s_waitcnt lgkmcnt(6)
	v_mfma_f32_32x32x16_bf16 v[68:83], v[252:255], v[172:175], v[68:83]
	ds_read_b128 v[252:255], v243 offset:32
	s_waitcnt lgkmcnt(6)
; #define MFMA32(a, b, c) __builtin_amdgcn_mfma_f32_32x32x16_bf16((a), (b), (c), 0, 0, 0)
; DI void attn_unit(unsigned char* smem, const Params& P, int bh, int qb) {
;     ...
;     if (active) {
; #pragma unroll
;       for (int a = 0; a < 2; ++a)
; #pragma unroll
;         for (int i = 0; i < 16; ++i) S[a][i] = -sref;
;       __builtin_amdgcn_s_setprio(1);
; #pragma unroll
;       for (int ks = 0; ks < 12; ++ks) {
;         const bf16x8 a0 = *(const bf16x8*)(cK + l31 * KLD + ks * 16 + hh * 8), a1 = *(const bf16x8*)(cK + (32 + l31) * KLD + ks * 16 + hh * 8);
;         S[0] = MFMA32(a0, qf[ks], S[0]); S[1] = MFMA32(a1, qf[ks], S[1]);
;       }
;       __builtin_amdgcn_s_setprio(0);
;     }
;     { const bf16_t* vp_ = vtb + (size_t)(tid >> 3) * 8192 + jt * 64 + (tid & 7) * 8; vr0 = *(const uint4*)(vp_ + (size_t)0 * 8192); vr1 = *(const uint4*)(vp_ + (size_t)32 * 8192); vr2 = *(const uint4*)(vp_ + (size_t)64 * 8192); vr3 = *(const uint4*)(vp_ + (size_t)96 * 8192); }
;     __builtin_amdgcn_sched_barrier(0);
	v_mfma_f32_32x32x16_bf16 v[52:67], v[180:183], v[172:175], v[52:67]
	s_waitcnt lgkmcnt(5)
	v_mfma_f32_32x32x16_bf16 v[4:19], v[184:187], v[172:175], v[4:19]
	s_waitcnt lgkmcnt(2)
	v_mfma_f32_32x32x16_bf16 v[36:51], v[244:247], v[100:103], v[20:35]
	ds_read_b128 v[244:247], v243 offset:12864
	v_lshl_add_u64 v[180:181], s[10:11], 1, v[198:199]
	v_add_co_u32_e32 v176, vcc, s78, v180
	s_nop 1
	v_addc_co_u32_e32 v177, vcc, 0, v181, vcc
	s_waitcnt lgkmcnt(2)
	v_mfma_f32_32x32x16_bf16 v[20:35], v[248:251], v[100:103], v[20:35]
	ds_read_b128 v[248:251], v243 offset:96
	v_add_co_u32_e32 v182, vcc, 0x100000, v180
	global_load_dwordx4 v[172:175], v[180:181], off
	s_nop 0
	global_load_dwordx4 v[176:179], v[176:177], off
	s_waitcnt lgkmcnt(2)
	v_mfma_f32_32x32x16_bf16 v[36:51], v[252:255], v[104:107], v[36:51]
	ds_read_b128 v[252:255], v243 offset:12896
	v_addc_co_u32_e32 v183, vcc, 0, v181, vcc
	v_add_co_u32_e32 v180, vcc, 0x180000, v180
	s_nop 1
	v_addc_co_u32_e32 v181, vcc, 0, v181, vcc
	s_waitcnt lgkmcnt(7)
	v_mfma_f32_32x32x16_bf16 v[20:35], v[226:229], v[104:107], v[20:35]
	ds_read_b128 v[226:229], v243 offset:128
	global_load_dwordx4 v[184:187], v[182:183], off
	s_nop 0
	global_load_dwordx4 v[180:183], v[180:181], off
	s_waitcnt lgkmcnt(7)
	v_mfma_f32_32x32x16_bf16 v[36:51], v[230:233], v[108:111], v[36:51]
	ds_read_b128 v[230:233], v243 offset:12928
	s_waitcnt lgkmcnt(4)
	v_mfma_f32_32x32x16_bf16 v[20:35], v[244:247], v[108:111], v[20:35]
	ds_read_b128 v[244:247], v243 offset:160
	s_waitcnt lgkmcnt(4)
	v_mfma_f32_32x32x16_bf16 v[36:51], v[248:251], v[112:115], v[36:51]
	ds_read_b128 v[248:251], v243 offset:12960
	s_waitcnt lgkmcnt(4)
	v_mfma_f32_32x32x16_bf16 v[20:35], v[252:255], v[112:115], v[20:35]
	ds_read_b128 v[252:255], v243 offset:192
	s_waitcnt lgkmcnt(4)
	v_mfma_f32_32x32x16_bf16 v[36:51], v[226:229], v[116:119], v[36:51]
	ds_read_b128 v[226:229], v243 offset:12992
	s_waitcnt lgkmcnt(4)
	v_mfma_f32_32x32x16_bf16 v[20:35], v[230:233], v[116:119], v[20:35]
	ds_read_b128 v[230:233], v243 offset:224
	s_waitcnt lgkmcnt(4)
	v_mfma_f32_32x32x16_bf16 v[36:51], v[244:247], v[120:123], v[36:51]
	ds_read_b128 v[244:247], v243 offset:13024
	s_waitcnt lgkmcnt(4)
	v_mfma_f32_32x32x16_bf16 v[20:35], v[248:251], v[120:123], v[20:35]
	ds_read_b128 v[248:251], v243 offset:256
	s_waitcnt lgkmcnt(4)
	v_mfma_f32_32x32x16_bf16 v[36:51], v[252:255], v[124:127], v[36:51]
	ds_read_b128 v[252:255], v243 offset:13056
	s_waitcnt lgkmcnt(4)
	v_mfma_f32_32x32x16_bf16 v[20:35], v[226:229], v[124:127], v[20:35]
	ds_read_b128 v[226:229], v243 offset:288
	s_waitcnt lgkmcnt(4)
	v_mfma_f32_32x32x16_bf16 v[36:51], v[230:233], v[128:131], v[36:51]
	ds_read_b128 v[230:233], v243 offset:13088
	s_waitcnt lgkmcnt(4)
	v_mfma_f32_32x32x16_bf16 v[20:35], v[244:247], v[128:131], v[20:35]
	ds_read_b128 v[244:247], v243 offset:320
	s_waitcnt lgkmcnt(4)
	v_mfma_f32_32x32x16_bf16 v[36:51], v[248:251], v[132:135], v[36:51]
	ds_read_b128 v[248:251], v243 offset:13120
	s_waitcnt lgkmcnt(4)
	v_mfma_f32_32x32x16_bf16 v[20:35], v[252:255], v[132:135], v[20:35]
	ds_read_b128 v[252:255], v243 offset:352
	s_waitcnt lgkmcnt(4)
	v_mfma_f32_32x32x16_bf16 v[36:51], v[226:229], v[136:139], v[36:51]
	ds_read_b128 v[226:229], v243 offset:13152
	s_waitcnt lgkmcnt(4)
	v_mfma_f32_32x32x16_bf16 v[20:35], v[230:233], v[136:139], v[20:35]
	s_barrier
	s_waitcnt lgkmcnt(3)
	v_mfma_f32_32x32x16_bf16 v[36:51], v[244:247], v[140:143], v[36:51]
	s_waitcnt lgkmcnt(2)
	v_mfma_f32_32x32x16_bf16 v[20:35], v[248:251], v[140:143], v[20:35]
	s_waitcnt lgkmcnt(1)
	v_mfma_f32_32x32x16_bf16 v[36:51], v[252:255], v[144:147], v[36:51]
	s_waitcnt lgkmcnt(0)
	v_mfma_f32_32x32x16_bf16 v[20:35], v[226:229], v[144:147], v[20:35]
	s_nop 11
	s_setprio 0
	s_branch .Lafter_ba_0

; DI int crow(int i, int h) { return (i & 3) + 8 * (i >> 2) + 4 * h; }
; DI void attn_unit(unsigned char* smem, const Params& P, int bh, int qb) {
;     ...
;     if (active) {
;       if (jt >= ntiles - 2) {
; #pragma unroll
;         for (int kt = 0; kt < 2; ++kt)
; #pragma unroll
;           for (int i = 0; i < 16; ++i) { const int key = jt * 64 + kt * 32 + crow(i, hh); if (key > qrow) S[kt][i] = -1e30f; }
;       }
.Lafter_ba_0:
	s_and_saveexec_b64 s[16:17], s[2:3]
	s_cbranch_execz .LBB0_496
	s_cmp_lt_u32 s21, s8
	s_cbranch_scc1 .LBB0_493
	v_add_u32_e32 v225, s20, v219
	v_add_u32_e32 v226, 64, v225
	v_cmp_le_i32_e32 vcc, v226, v188
	s_nop 1
	v_cndmask_b32_e32 v36, v213, v36, vcc
	v_cmp_lt_i32_e32 vcc, v226, v188
	v_add_u32_e32 v226, 0x42, v225
	s_nop 0
	v_cndmask_b32_e32 v37, v213, v37, vcc
	v_cmp_le_i32_e32 vcc, v226, v188
	v_add_u32_e32 v226, 0x43, v225
	s_nop 0
	v_cndmask_b32_e32 v38, v213, v38, vcc
	v_cmp_le_i32_e32 vcc, v226, v188
	v_add_u32_e32 v226, 0x48, v225
	s_nop 0
	v_cndmask_b32_e32 v39, v213, v39, vcc
	v_cmp_le_i32_e32 vcc, v226, v188
	v_add_u32_e32 v226, 0x49, v225
	s_nop 0
	v_cndmask_b32_e32 v40, v213, v40, vcc
	v_cmp_le_i32_e32 vcc, v226, v188
	v_add_u32_e32 v226, 0x4a, v225
	s_nop 0
	v_cndmask_b32_e32 v41, v213, v41, vcc
	v_cmp_le_i32_e32 vcc, v226, v188
	v_add_u32_e32 v226, 0x4b, v225
	s_nop 0
	v_cndmask_b32_e32 v42, v213, v42, vcc
	v_cmp_le_i32_e32 vcc, v226, v188
	v_add_u32_e32 v226, 0x50, v225
	s_nop 0
	v_cndmask_b32_e32 v43, v213, v43, vcc
	v_cmp_le_i32_e32 vcc, v226, v188
	v_add_u32_e32 v226, 0x51, v225
	s_nop 0
	v_cndmask_b32_e32 v44, v213, v44, vcc
	v_cmp_le_i32_e32 vcc, v226, v188
	v_add_u32_e32 v226, 0x52, v225
	s_nop 0
	v_cndmask_b32_e32 v45, v213, v45, vcc
	v_cmp_le_i32_e32 vcc, v226, v188
	v_add_u32_e32 v226, 0x53, v225
	s_nop 0
	v_cndmask_b32_e32 v46, v213, v46, vcc
	v_cmp_le_i32_e32 vcc, v226, v188
	v_add_u32_e32 v226, 0x58, v225
	s_nop 0
	v_cndmask_b32_e32 v47, v213, v47, vcc
	v_cmp_le_i32_e32 vcc, v226, v188
	v_add_u32_e32 v226, 0x59, v225
	s_nop 0
	v_cndmask_b32_e32 v48, v213, v48, vcc
	v_cmp_le_i32_e32 vcc, v226, v188
	v_add_u32_e32 v226, 0x5a, v225
	s_nop 0
	v_cndmask_b32_e32 v49, v213, v49, vcc
	v_cmp_le_i32_e32 vcc, v226, v188
	v_add_u32_e32 v226, 0x5b, v225
	s_nop 0
	v_cndmask_b32_e32 v50, v213, v50, vcc
	v_cmp_le_i32_e32 vcc, v226, v188
	v_add_u32_e32 v226, 0x60, v225
	s_nop 0
	v_cndmask_b32_e32 v51, v213, v51, vcc
	v_cmp_le_i32_e32 vcc, v226, v188
	v_add_u32_e32 v226, 0x61, v225
	s_nop 0
	v_cndmask_b32_e32 v20, v213, v20, vcc
	v_cmp_le_i32_e32 vcc, v226, v188
	v_add_u32_e32 v226, 0x62, v225
	s_nop 0
	v_cndmask_b32_e32 v21, v213, v21, vcc
	v_cmp_le_i32_e32 vcc, v226, v188
	v_add_u32_e32 v226, 0x63, v225
	s_nop 0
	v_cndmask_b32_e32 v22, v213, v22, vcc
	v_cmp_le_i32_e32 vcc, v226, v188
	v_add_u32_e32 v226, 0x68, v225
	s_nop 0
	v_cndmask_b32_e32 v23, v213, v23, vcc
	v_cmp_le_i32_e32 vcc, v226, v188
	v_add_u32_e32 v226, 0x69, v225
	s_nop 0
	v_cndmask_b32_e32 v24, v213, v24, vcc
	v_cmp_le_i32_e32 vcc, v226, v188
	v_add_u32_e32 v226, 0x6a, v225
	s_nop 0
	v_cndmask_b32_e32 v25, v213, v25, vcc
	v_cmp_le_i32_e32 vcc, v226, v188
	v_add_u32_e32 v226, 0x6b, v225
	s_nop 0
	v_cndmask_b32_e32 v26, v213, v26, vcc
	v_cmp_le_i32_e32 vcc, v226, v188
	v_add_u32_e32 v226, 0x70, v225
	s_nop 0
	v_cndmask_b32_e32 v27, v213, v27, vcc
	v_cmp_le_i32_e32 vcc, v226, v188
	v_add_u32_e32 v226, 0x71, v225
	s_nop 0
	v_cndmask_b32_e32 v28, v213, v28, vcc
	v_cmp_le_i32_e32 vcc, v226, v188
	v_add_u32_e32 v226, 0x72, v225
	s_nop 0
	v_cndmask_b32_e32 v29, v213, v29, vcc
	v_cmp_le_i32_e32 vcc, v226, v188
	v_add_u32_e32 v226, 0x73, v225
	s_nop 0
	v_cndmask_b32_e32 v30, v213, v30, vcc
	v_cmp_le_i32_e32 vcc, v226, v188
	v_add_u32_e32 v226, 0x78, v225
	s_nop 0
	v_cndmask_b32_e32 v31, v213, v31, vcc
	v_cmp_le_i32_e32 vcc, v226, v188
	v_add_u32_e32 v226, 0x79, v225
	s_nop 0
	v_cndmask_b32_e32 v32, v213, v32, vcc
	v_cmp_le_i32_e32 vcc, v226, v188
	v_add_u32_e32 v226, 0x7a, v225
	v_add_u32_e32 v225, 0x7b, v225
	v_cndmask_b32_e32 v33, v213, v33, vcc
	v_cmp_le_i32_e32 vcc, v226, v188
	s_nop 1
	v_cndmask_b32_e32 v34, v213, v34, vcc
	v_cmp_le_i32_e32 vcc, v225, v188
	s_nop 1
	v_cndmask_b32_e32 v35, v213, v35, vcc

; #define MFMA32(a, b, c) __builtin_amdgcn_mfma_f32_32x32x16_bf16((a), (b), (c), 0, 0, 0)
; DI void attn_unit(unsigned char* smem, const Params& P, int bh, int qb) {
;     ...
;     if (more) {
;       const bf16_t* kp = kbuf + (size_t)(jt + 1) * 64 * 192;
;       kr0 = *(const uint4*)(kp + kgo + 0); kr1 = *(const uint4*)(kp + kgo + 32); kr2 = *(const uint4*)(kp + kgo + 64); kr3 = *(const uint4*)(kp + kgo + 96); kr4 = *(const uint4*)(kp + kgo + 128); kr5 = *(const uint4*)(kp + kgo + 160);
;     }
;     __builtin_amdgcn_sched_barrier(0);
;     f32x16 S[2];
;     const float sref = (jt == 0) ? 0.f : mrun;
;     if (active) {
; #pragma unroll
;       for (int a = 0; a < 2; ++a)
; #pragma unroll
;         for (int i = 0; i < 16; ++i) S[a][i] = -sref;
;       __builtin_amdgcn_s_setprio(1);
; #pragma unroll
;       for (int ks = 0; ks < 12; ++ks) {
;         const bf16x8 a0 = *(const bf16x8*)(cK + l31 * KLD + ks * 16 + hh * 8), a1 = *(const bf16x8*)(cK + (32 + l31) * KLD + ks * 16 + hh * 8);
;         S[0] = MFMA32(a0, qf[ks], S[0]); S[1] = MFMA32(a1, qf[ks], S[1]);
;       }
;     ...
;     if (active) {
;       __builtin_amdgcn_s_setprio(1);
; #pragma unroll
;       for (int kt = 0; kt < 2; ++kt)
; #pragma unroll
;         for (int s2 = 0; s2 < 2; ++s2) {
;           uint4 pp; pp.x = pk2(S[kt][8 * s2], S[kt][8 * s2 + 1]); pp.y = pk2(S[kt][8 * s2 + 2], S[kt][8 * s2 + 3]);
;           pp.z = pk2(S[kt][8 * s2 + 4], S[kt][8 * s2 + 5]); pp.w = pk2(S[kt][8 * s2 + 6], S[kt][8 * s2 + 7]);
;           const bf16x8 pb = __builtin_bit_cast(bf16x8, pp);
; #pragma unroll
;           for (int d = 0; d < 4; ++d) {
;             const bf16x8 vf = *(const bf16x8*)(sV + (d * 32 + l31) * LDK + kt * 32 + s2 * 16 + hh * 8);
;             O[d] = MFMA32(vf, pb, O[d]);
;           }
;         }
;       __builtin_amdgcn_s_setprio(0);
;     }
.LBB0_518:
	s_add_i32 s22, s20, 2
	s_bitcmp0_b32 s22, 0
	s_cselect_b64 s[16:17], -1, 0
	s_add_i32 s10, s21, 64
	v_cmp_le_i32_e64 s[2:3], s10, v221
	v_cmp_le_i32_e64 s[98:99], s21, v221
	s_cmp_lg_u64 s[2:3], 0
	s_cbranch_scc0 .Lslow_1
	s_and_b64 s[24:25], s[16:17], exec
	s_cselect_b32 s23, s9, s28
	v_add3_u32 v243, s23, v199, v215
	s_setprio 1
	ds_read_b128 v[12:15], v222 offset:25600
	ds_read_b128 v[186:189], v223 offset:25600
	ds_read_b128 v[226:229], v224 offset:25600
	ds_read_b128 v[230:233], v225 offset:25600
	ds_read_b128 v[244:247], v222 offset:25632
	ds_read_b128 v[248:251], v223 offset:25632
	ds_read_b128 v[252:255], v224 offset:25632
	v_cvt_pk_bf16_f32 v8, v34, v35
	v_cvt_pk_bf16_f32 v9, v36, v37
	v_cvt_pk_bf16_f32 v10, v38, v39
	v_cvt_pk_bf16_f32 v11, v40, v41
	v_cvt_pk_bf16_f32 v4, v42, v43
	v_cvt_pk_bf16_f32 v5, v44, v45
	v_cvt_pk_bf16_f32 v6, v46, v47
	v_cvt_pk_bf16_f32 v7, v48, v49
	s_waitcnt lgkmcnt(6)
	v_mfma_f32_32x32x16_bf16 v[98:113], v[12:15], v[8:11], v[98:113]
	ds_read_b128 v[12:15], v225 offset:25632
	global_load_dwordx4 v[162:165], v[16:17], off
	s_waitcnt lgkmcnt(6)
	v_mfma_f32_32x32x16_bf16 v[82:97], v[186:189], v[8:11], v[82:97]
	ds_read_b128 v[186:189], v222 offset:25664
	global_load_dwordx4 v[166:169], v[16:17], off offset:64
	s_waitcnt lgkmcnt(6)
	v_mfma_f32_32x32x16_bf16 v[66:81], v[226:229], v[8:11], v[66:81]
	ds_read_b128 v[226:229], v223 offset:25664
	global_load_dwordx4 v[170:173], v[16:17], off offset:128
	s_waitcnt lgkmcnt(6)
	v_mfma_f32_32x32x16_bf16 v[50:65], v[230:233], v[8:11], v[50:65]
	ds_read_b128 v[230:233], v224 offset:25664
	global_load_dwordx4 v[174:177], v[16:17], off offset:192
	s_waitcnt lgkmcnt(6)
	v_mfma_f32_32x32x16_bf16 v[98:113], v[244:247], v[4:7], v[98:113]
	ds_read_b128 v[244:247], v225 offset:25664
	global_load_dwordx4 v[178:181], v[16:17], off offset:256
	v_cvt_pk_bf16_f32 v8, v18, v19
	v_cvt_pk_bf16_f32 v9, v20, v21
	v_cvt_pk_bf16_f32 v10, v22, v23
	v_cvt_pk_bf16_f32 v11, v24, v25
	s_waitcnt lgkmcnt(6)
	v_mfma_f32_32x32x16_bf16 v[82:97], v[248:251], v[4:7], v[82:97]
	ds_read_b128 v[248:251], v222 offset:25696
	global_load_dwordx4 v[182:185], v[16:17], off offset:320
	s_waitcnt lgkmcnt(6)
	v_mfma_f32_32x32x16_bf16 v[66:81], v[252:255], v[4:7], v[66:81]
	ds_read_b128 v[252:255], v223 offset:25696
	s_waitcnt lgkmcnt(6)
	v_mfma_f32_32x32x16_bf16 v[50:65], v[12:15], v[4:7], v[50:65]
	ds_read_b128 v[12:15], v224 offset:25696
	s_waitcnt lgkmcnt(6)
	v_mfma_f32_32x32x16_bf16 v[98:113], v[186:189], v[8:11], v[98:113]
	ds_read_b128 v[186:189], v225 offset:25696
	v_cvt_pk_bf16_f32 v4, v26, v27
	v_cvt_pk_bf16_f32 v5, v28, v29
	v_cvt_pk_bf16_f32 v6, v30, v31
	v_cvt_pk_bf16_f32 v7, v32, v33
	s_waitcnt lgkmcnt(6)
	v_mfma_f32_32x32x16_bf16 v[82:97], v[226:229], v[8:11], v[82:97]
	v_xor_b32_e32 v18, 0x80000000, v202
	v_mov_b32_e32 v19, v18
	v_mov_b32_e32 v20, v18
	v_mov_b32_e32 v21, v18
	ds_read_b128 v[226:229], v243 offset:12832
	s_waitcnt lgkmcnt(6)
	v_mfma_f32_32x32x16_bf16 v[66:81], v[230:233], v[8:11], v[66:81]
	v_mov_b32_e32 v22, v18
	v_mov_b32_e32 v23, v18
	v_mov_b32_e32 v24, v18
	v_mov_b32_e32 v25, v18
	ds_read_b128 v[230:233], v243 offset:64
	s_waitcnt lgkmcnt(6)
	v_mfma_f32_32x32x16_bf16 v[50:65], v[244:247], v[8:11], v[50:65]
	v_mov_b32_e32 v26, v18
	v_mov_b32_e32 v27, v18
	v_mov_b32_e32 v28, v18
	v_mov_b32_e32 v29, v18
	ds_read_b128 v[244:247], v243
	s_waitcnt lgkmcnt(6)
	v_mfma_f32_32x32x16_bf16 v[98:113], v[248:251], v[4:7], v[98:113]
	v_mov_b32_e32 v30, v18
	v_mov_b32_e32 v31, v18
	v_mov_b32_e32 v32, v18
	v_mov_b32_e32 v33, v18
	ds_read_b128 v[248:251], v243 offset:12800
	s_waitcnt lgkmcnt(6)
	v_mfma_f32_32x32x16_bf16 v[82:97], v[252:255], v[4:7], v[82:97]
	ds_read_b128 v[252:255], v243 offset:32
	s_waitcnt lgkmcnt(6)
	v_mfma_f32_32x32x16_bf16 v[66:81], v[12:15], v[4:7], v[66:81]
	s_waitcnt lgkmcnt(5)
	v_mfma_f32_32x32x16_bf16 v[50:65], v[186:189], v[4:7], v[50:65]
	s_waitcnt lgkmcnt(2)
	v_mfma_f32_32x32x16_bf16 v[34:49], v[244:247], v[114:117], v[18:33]
	ds_read_b128 v[244:247], v243 offset:12864
	v_lshl_add_u64 v[12:13], s[10:11], 1, v[200:201]
	v_add_co_u32_e32 v8, vcc, s78, v12
	s_nop 1
	v_addc_co_u32_e32 v9, vcc, 0, v13, vcc
	s_waitcnt lgkmcnt(2)
	v_mfma_f32_32x32x16_bf16 v[18:33], v[248:251], v[114:117], v[18:33]
	ds_read_b128 v[248:251], v243 offset:96
	v_add_co_u32_e32 v14, vcc, 0x100000, v12
	global_load_dwordx4 v[4:7], v[12:13], off
	s_nop 0
	global_load_dwordx4 v[8:11], v[8:9], off
	s_waitcnt lgkmcnt(2)
	v_mfma_f32_32x32x16_bf16 v[34:49], v[252:255], v[118:121], v[34:49]
	ds_read_b128 v[252:255], v243 offset:12896
	v_addc_co_u32_e32 v15, vcc, 0, v13, vcc
	v_add_co_u32_e32 v12, vcc, 0x180000, v12
	s_nop 1
	v_addc_co_u32_e32 v13, vcc, 0, v13, vcc
	s_waitcnt lgkmcnt(7)
	v_mfma_f32_32x32x16_bf16 v[18:33], v[226:229], v[118:121], v[18:33]
	ds_read_b128 v[226:229], v243 offset:128
	global_load_dwordx4 v[186:189], v[14:15], off
	s_nop 0
	global_load_dwordx4 v[12:15], v[12:13], off
	s_waitcnt lgkmcnt(7)
	v_mfma_f32_32x32x16_bf16 v[34:49], v[230:233], v[122:125], v[34:49]
	ds_read_b128 v[230:233], v243 offset:12928
	s_waitcnt lgkmcnt(4)
	v_mfma_f32_32x32x16_bf16 v[18:33], v[244:247], v[122:125], v[18:33]
	ds_read_b128 v[244:247], v243 offset:160
	s_waitcnt lgkmcnt(4)
	v_mfma_f32_32x32x16_bf16 v[34:49], v[248:251], v[126:129], v[34:49]
	ds_read_b128 v[248:251], v243 offset:12960
	s_waitcnt lgkmcnt(4)
	v_mfma_f32_32x32x16_bf16 v[18:33], v[252:255], v[126:129], v[18:33]
	ds_read_b128 v[252:255], v243 offset:192
	s_waitcnt lgkmcnt(4)
	v_mfma_f32_32x32x16_bf16 v[34:49], v[226:229], v[130:133], v[34:49]
	ds_read_b128 v[226:229], v243 offset:12992
	s_waitcnt lgkmcnt(4)
	v_mfma_f32_32x32x16_bf16 v[18:33], v[230:233], v[130:133], v[18:33]
	ds_read_b128 v[230:233], v243 offset:224
	s_waitcnt lgkmcnt(4)
	v_mfma_f32_32x32x16_bf16 v[34:49], v[244:247], v[134:137], v[34:49]
	ds_read_b128 v[244:247], v243 offset:13024
	s_waitcnt lgkmcnt(4)
	v_mfma_f32_32x32x16_bf16 v[18:33], v[248:251], v[134:137], v[18:33]
	ds_read_b128 v[248:251], v243 offset:256
	s_waitcnt lgkmcnt(4)
	v_mfma_f32_32x32x16_bf16 v[34:49], v[252:255], v[138:141], v[34:49]
	ds_read_b128 v[252:255], v243 offset:13056
	s_waitcnt lgkmcnt(4)
	v_mfma_f32_32x32x16_bf16 v[18:33], v[226:229], v[138:141], v[18:33]
	ds_read_b128 v[226:229], v243 offset:288
	s_waitcnt lgkmcnt(4)
	v_mfma_f32_32x32x16_bf16 v[34:49], v[230:233], v[142:145], v[34:49]
	ds_read_b128 v[230:233], v243 offset:13088
	s_waitcnt lgkmcnt(4)
	v_mfma_f32_32x32x16_bf16 v[18:33], v[244:247], v[142:145], v[18:33]
	ds_read_b128 v[244:247], v243 offset:320
	s_waitcnt lgkmcnt(4)
	v_mfma_f32_32x32x16_bf16 v[34:49], v[248:251], v[146:149], v[34:49]
	ds_read_b128 v[248:251], v243 offset:13120
	s_waitcnt lgkmcnt(4)
	v_mfma_f32_32x32x16_bf16 v[18:33], v[252:255], v[146:149], v[18:33]
	ds_read_b128 v[252:255], v243 offset:352
	s_waitcnt lgkmcnt(4)
	v_mfma_f32_32x32x16_bf16 v[34:49], v[226:229], v[150:153], v[34:49]
	ds_read_b128 v[226:229], v243 offset:13152
	s_waitcnt lgkmcnt(4)
	v_mfma_f32_32x32x16_bf16 v[18:33], v[230:233], v[150:153], v[18:33]
	s_barrier
; #define MFMA32(a, b, c) __builtin_amdgcn_mfma_f32_32x32x16_bf16((a), (b), (c), 0, 0, 0)
; DI void attn_unit(unsigned char* smem, const Params& P, int bh, int qb) {
;     ...
;       __builtin_amdgcn_s_setprio(1);
; #pragma unroll
;       for (int ks = 0; ks < 12; ++ks) {
;         const bf16x8 a0 = *(const bf16x8*)(cK + l31 * KLD + ks * 16 + hh * 8), a1 = *(const bf16x8*)(cK + (32 + l31) * KLD + ks * 16 + hh * 8);
;         S[0] = MFMA32(a0, qf[ks], S[0]); S[1] = MFMA32(a1, qf[ks], S[1]);
;       }
;       __builtin_amdgcn_s_setprio(0);
;     }
	s_waitcnt lgkmcnt(3)
	v_mfma_f32_32x32x16_bf16 v[34:49], v[244:247], v[154:157], v[34:49]
	s_waitcnt lgkmcnt(2)
	v_mfma_f32_32x32x16_bf16 v[18:33], v[248:251], v[154:157], v[18:33]
	s_waitcnt lgkmcnt(1)
	v_mfma_f32_32x32x16_bf16 v[34:49], v[252:255], v[158:161], v[34:49]
	s_waitcnt lgkmcnt(0)
	v_mfma_f32_32x32x16_bf16 v[18:33], v[226:229], v[158:161], v[18:33]
	s_nop 11
	s_setprio 0
	s_branch .Lafter_ba_1

; DI int crow(int i, int h) { return (i & 3) + 8 * (i >> 2) + 4 * h; }
; DI void attn_unit(unsigned char* smem, const Params& P, int bh, int qb) {
;     ...
;       if (jt >= ntiles - 2) {
; #pragma unroll
;         for (int kt = 0; kt < 2; ++kt)
; #pragma unroll
;           for (int i = 0; i < 16; ++i) { const int key = jt * 64 + kt * 32 + crow(i, hh); if (key > qrow) S[kt][i] = -1e30f; }
;       }
.Lafter_ba_1:
	s_and_saveexec_b64 s[18:19], s[2:3]
	s_cbranch_execz .LBB0_526
	s_cmp_lt_u32 s22, s8
	s_cbranch_scc1 .LBB0_523
	v_add_u32_e32 v226, s21, v216
	v_add_u32_e32 v227, 64, v226
	v_cmp_le_i32_e32 vcc, v227, v196
	s_nop 1
	v_cndmask_b32_e32 v34, v213, v34, vcc
	v_cmp_lt_i32_e32 vcc, v227, v196
	v_add_u32_e32 v227, 0x42, v226
	s_nop 0
	v_cndmask_b32_e32 v35, v213, v35, vcc
	v_cmp_le_i32_e32 vcc, v227, v196
	v_add_u32_e32 v227, 0x43, v226
	s_nop 0
	v_cndmask_b32_e32 v36, v213, v36, vcc
	v_cmp_le_i32_e32 vcc, v227, v196
	v_add_u32_e32 v227, 0x48, v226
	s_nop 0
	v_cndmask_b32_e32 v37, v213, v37, vcc
	v_cmp_le_i32_e32 vcc, v227, v196
	v_add_u32_e32 v227, 0x49, v226
	s_nop 0
	v_cndmask_b32_e32 v38, v213, v38, vcc
	v_cmp_le_i32_e32 vcc, v227, v196
	v_add_u32_e32 v227, 0x4a, v226
	s_nop 0
	v_cndmask_b32_e32 v39, v213, v39, vcc
	v_cmp_le_i32_e32 vcc, v227, v196
	v_add_u32_e32 v227, 0x4b, v226
	s_nop 0
	v_cndmask_b32_e32 v40, v213, v40, vcc
	v_cmp_le_i32_e32 vcc, v227, v196
	v_add_u32_e32 v227, 0x50, v226
	s_nop 0
	v_cndmask_b32_e32 v41, v213, v41, vcc
	v_cmp_le_i32_e32 vcc, v227, v196
	v_add_u32_e32 v227, 0x51, v226
	s_nop 0
	v_cndmask_b32_e32 v42, v213, v42, vcc
	v_cmp_le_i32_e32 vcc, v227, v196
	v_add_u32_e32 v227, 0x52, v226
	s_nop 0
	v_cndmask_b32_e32 v43, v213, v43, vcc
	v_cmp_le_i32_e32 vcc, v227, v196
	v_add_u32_e32 v227, 0x53, v226
	s_nop 0
	v_cndmask_b32_e32 v44, v213, v44, vcc
	v_cmp_le_i32_e32 vcc, v227, v196
	v_add_u32_e32 v227, 0x58, v226
	s_nop 0
	v_cndmask_b32_e32 v45, v213, v45, vcc
	v_cmp_le_i32_e32 vcc, v227, v196
	v_add_u32_e32 v227, 0x59, v226
	s_nop 0
	v_cndmask_b32_e32 v46, v213, v46, vcc
	v_cmp_le_i32_e32 vcc, v227, v196
	v_add_u32_e32 v227, 0x5a, v226
	s_nop 0
	v_cndmask_b32_e32 v47, v213, v47, vcc
	v_cmp_le_i32_e32 vcc, v227, v196
	v_add_u32_e32 v227, 0x5b, v226
	s_nop 0
	v_cndmask_b32_e32 v48, v213, v48, vcc
	v_cmp_le_i32_e32 vcc, v227, v196
	v_add_u32_e32 v227, 0x60, v226
	s_nop 0
	v_cndmask_b32_e32 v49, v213, v49, vcc
	v_cmp_le_i32_e32 vcc, v227, v196
	v_add_u32_e32 v227, 0x61, v226
	s_nop 0
	v_cndmask_b32_e32 v18, v213, v18, vcc
	v_cmp_le_i32_e32 vcc, v227, v196
	v_add_u32_e32 v227, 0x62, v226
	s_nop 0
	v_cndmask_b32_e32 v19, v213, v19, vcc
	v_cmp_le_i32_e32 vcc, v227, v196
	v_add_u32_e32 v227, 0x63, v226
	s_nop 0
	v_cndmask_b32_e32 v20, v213, v20, vcc
	v_cmp_le_i32_e32 vcc, v227, v196
	v_add_u32_e32 v227, 0x68, v226
	s_nop 0
	v_cndmask_b32_e32 v21, v213, v21, vcc
	v_cmp_le_i32_e32 vcc, v227, v196
	v_add_u32_e32 v227, 0x69, v226
	s_nop 0
	v_cndmask_b32_e32 v22, v213, v22, vcc
	v_cmp_le_i32_e32 vcc, v227, v196
	v_add_u32_e32 v227, 0x6a, v226
	s_nop 0
	v_cndmask_b32_e32 v23, v213, v23, vcc
	v_cmp_le_i32_e32 vcc, v227, v196
	v_add_u32_e32 v227, 0x6b, v226
	s_nop 0
	v_cndmask_b32_e32 v24, v213, v24, vcc
	v_cmp_le_i32_e32 vcc, v227, v196
	v_add_u32_e32 v227, 0x70, v226
	s_nop 0
	v_cndmask_b32_e32 v25, v213, v25, vcc
	v_cmp_le_i32_e32 vcc, v227, v196
	v_add_u32_e32 v227, 0x71, v226
	s_nop 0
	v_cndmask_b32_e32 v26, v213, v26, vcc
	v_cmp_le_i32_e32 vcc, v227, v196
	v_add_u32_e32 v227, 0x72, v226
	s_nop 0
	v_cndmask_b32_e32 v27, v213, v27, vcc
	v_cmp_le_i32_e32 vcc, v227, v196
	v_add_u32_e32 v227, 0x73, v226
	s_nop 0
	v_cndmask_b32_e32 v28, v213, v28, vcc
	v_cmp_le_i32_e32 vcc, v227, v196
	v_add_u32_e32 v227, 0x78, v226
	s_nop 0
	v_cndmask_b32_e32 v29, v213, v29, vcc
	v_cmp_le_i32_e32 vcc, v227, v196
	v_add_u32_e32 v227, 0x79, v226
	s_nop 0
	v_cndmask_b32_e32 v30, v213, v30, vcc
	v_cmp_le_i32_e32 vcc, v227, v196
	v_add_u32_e32 v227, 0x7a, v226
	v_add_u32_e32 v226, 0x7b, v226
	v_cndmask_b32_e32 v31, v213, v31, vcc
	v_cmp_le_i32_e32 vcc, v227, v196
	s_nop 1
	v_cndmask_b32_e32 v32, v213, v32, vcc
	v_cmp_le_i32_e32 vcc, v226, v196
	s_nop 1
	v_cndmask_b32_e32 v33, v213, v33, vcc

; #define MFMA32(a, b, c) __builtin_amdgcn_mfma_f32_32x32x16_bf16((a), (b), (c), 0, 0, 0)
; DI void attn_unit(unsigned char* smem, const Params& P, int bh, int qb) {
;     ...
;     if (more) {
;       const bf16_t* kp = kbuf + (size_t)(jt + 1) * 64 * 192;
;       kr0 = *(const uint4*)(kp + kgo + 0); kr1 = *(const uint4*)(kp + kgo + 32); kr2 = *(const uint4*)(kp + kgo + 64); kr3 = *(const uint4*)(kp + kgo + 96); kr4 = *(const uint4*)(kp + kgo + 128); kr5 = *(const uint4*)(kp + kgo + 160);
;     }
;     __builtin_amdgcn_sched_barrier(0);
;     f32x16 S[2];
;     const float sref = (jt == 0) ? 0.f : mrun;
;     if (active) {
; #pragma unroll
;       for (int a = 0; a < 2; ++a)
; #pragma unroll
;         for (int i = 0; i < 16; ++i) S[a][i] = -sref;
;       __builtin_amdgcn_s_setprio(1);
; #pragma unroll
;       for (int ks = 0; ks < 12; ++ks) {
;         const bf16x8 a0 = *(const bf16x8*)(cK + l31 * KLD + ks * 16 + hh * 8), a1 = *(const bf16x8*)(cK + (32 + l31) * KLD + ks * 16 + hh * 8);
;         S[0] = MFMA32(a0, qf[ks], S[0]); S[1] = MFMA32(a1, qf[ks], S[1]);
;       }
;     ...
;     if (active) {
;       __builtin_amdgcn_s_setprio(1);
; #pragma unroll
;       for (int kt = 0; kt < 2; ++kt)
; #pragma unroll
;         for (int s2 = 0; s2 < 2; ++s2) {
;           uint4 pp; pp.x = pk2(S[kt][8 * s2], S[kt][8 * s2 + 1]); pp.y = pk2(S[kt][8 * s2 + 2], S[kt][8 * s2 + 3]);
;           pp.z = pk2(S[kt][8 * s2 + 4], S[kt][8 * s2 + 5]); pp.w = pk2(S[kt][8 * s2 + 6], S[kt][8 * s2 + 7]);
;           const bf16x8 pb = __builtin_bit_cast(bf16x8, pp);
; #pragma unroll
;           for (int d = 0; d < 4; ++d) {
;             const bf16x8 vf = *(const bf16x8*)(sV + (d * 32 + l31) * LDK + kt * 32 + s2 * 16 + hh * 8);
;             O[d] = MFMA32(vf, pb, O[d]);
;           }
;         }
;       __builtin_amdgcn_s_setprio(0);
;     }
.LBB0_1409:
	s_add_i32 s22, s20, 0x80
	s_bitcmp0_b32 s22, 0
	s_cselect_b64 s[14:15], -1, 0
	s_add_i32 s10, s21, 64
	v_cmp_le_i32_e64 s[2:3], s10, v220
	v_cmp_le_i32_e64 s[98:99], s21, v220
	s_cmp_lg_u64 s[2:3], 0
	s_cbranch_scc0 .Lslow_2
	s_and_b64 s[24:25], s[14:15], exec
	s_cselect_b32 s23, s9, s28
	v_add3_u32 v243, s23, v197, v201
	s_setprio 1
	ds_read_b128 v[180:183], v221 offset:25600
	ds_read_b128 v[184:187], v222 offset:25600
	ds_read_b128 v[226:229], v223 offset:25600
	ds_read_b128 v[230:233], v224 offset:25600
	ds_read_b128 v[244:247], v221 offset:25632
	ds_read_b128 v[248:251], v222 offset:25632
	ds_read_b128 v[252:255], v223 offset:25632
	v_cvt_pk_bf16_f32 v176, v36, v37
	v_cvt_pk_bf16_f32 v177, v38, v39
	v_cvt_pk_bf16_f32 v178, v40, v41
	v_cvt_pk_bf16_f32 v179, v42, v43
	v_cvt_pk_bf16_f32 v172, v44, v45
	v_cvt_pk_bf16_f32 v173, v46, v47
	v_cvt_pk_bf16_f32 v174, v48, v49
	v_cvt_pk_bf16_f32 v175, v50, v51
	s_waitcnt lgkmcnt(6)
	v_mfma_f32_32x32x16_bf16 v[84:99], v[180:183], v[176:179], v[84:99]
	ds_read_b128 v[180:183], v224 offset:25632
	global_load_dwordx4 v[148:151], v[202:203], off
	s_waitcnt lgkmcnt(6)
	v_mfma_f32_32x32x16_bf16 v[68:83], v[184:187], v[176:179], v[68:83]
	ds_read_b128 v[184:187], v221 offset:25664
	global_load_dwordx4 v[152:155], v[202:203], off offset:64
	s_waitcnt lgkmcnt(6)
	v_mfma_f32_32x32x16_bf16 v[52:67], v[226:229], v[176:179], v[52:67]
	ds_read_b128 v[226:229], v222 offset:25664
	global_load_dwordx4 v[156:159], v[202:203], off offset:128
	s_waitcnt lgkmcnt(6)
	v_mfma_f32_32x32x16_bf16 v[4:19], v[230:233], v[176:179], v[4:19]
	ds_read_b128 v[230:233], v223 offset:25664
	global_load_dwordx4 v[160:163], v[202:203], off offset:192
	s_waitcnt lgkmcnt(6)
	v_mfma_f32_32x32x16_bf16 v[84:99], v[244:247], v[172:175], v[84:99]
	ds_read_b128 v[244:247], v224 offset:25664
	global_load_dwordx4 v[164:167], v[202:203], off offset:256
	v_cvt_pk_bf16_f32 v176, v20, v21
	v_cvt_pk_bf16_f32 v177, v22, v23
	v_cvt_pk_bf16_f32 v178, v24, v25
	v_cvt_pk_bf16_f32 v179, v26, v27
	s_waitcnt lgkmcnt(6)
	v_mfma_f32_32x32x16_bf16 v[68:83], v[248:251], v[172:175], v[68:83]
	ds_read_b128 v[248:251], v221 offset:25696
	global_load_dwordx4 v[168:171], v[202:203], off offset:320
	s_waitcnt lgkmcnt(6)
	v_mfma_f32_32x32x16_bf16 v[52:67], v[252:255], v[172:175], v[52:67]
	ds_read_b128 v[252:255], v222 offset:25696
	s_waitcnt lgkmcnt(6)
	v_mfma_f32_32x32x16_bf16 v[4:19], v[180:183], v[172:175], v[4:19]
	ds_read_b128 v[180:183], v223 offset:25696
	s_waitcnt lgkmcnt(6)
	v_mfma_f32_32x32x16_bf16 v[84:99], v[184:187], v[176:179], v[84:99]
	ds_read_b128 v[184:187], v224 offset:25696
	v_cvt_pk_bf16_f32 v172, v28, v29
	v_cvt_pk_bf16_f32 v173, v30, v31
	v_cvt_pk_bf16_f32 v174, v32, v33
	v_cvt_pk_bf16_f32 v175, v34, v35
	s_waitcnt lgkmcnt(6)
	v_mfma_f32_32x32x16_bf16 v[68:83], v[226:229], v[176:179], v[68:83]
	v_xor_b32_e32 v20, 0x80000000, v200
	v_mov_b32_e32 v21, v20
	v_mov_b32_e32 v22, v20
	v_mov_b32_e32 v23, v20
	ds_read_b128 v[226:229], v243 offset:12832
	s_waitcnt lgkmcnt(6)
	v_mfma_f32_32x32x16_bf16 v[52:67], v[230:233], v[176:179], v[52:67]
	v_mov_b32_e32 v24, v20
	v_mov_b32_e32 v25, v20
	v_mov_b32_e32 v26, v20
	v_mov_b32_e32 v27, v20
	ds_read_b128 v[230:233], v243 offset:64
	s_waitcnt lgkmcnt(6)
	v_mfma_f32_32x32x16_bf16 v[4:19], v[244:247], v[176:179], v[4:19]
	v_mov_b32_e32 v28, v20
	v_mov_b32_e32 v29, v20
	v_mov_b32_e32 v30, v20
	v_mov_b32_e32 v31, v20
	ds_read_b128 v[244:247], v243
	s_waitcnt lgkmcnt(6)
	v_mfma_f32_32x32x16_bf16 v[84:99], v[248:251], v[172:175], v[84:99]
	v_mov_b32_e32 v32, v20
	v_mov_b32_e32 v33, v20
	v_mov_b32_e32 v34, v20
	v_mov_b32_e32 v35, v20
	ds_read_b128 v[248:251], v243 offset:12800
	s_waitcnt lgkmcnt(6)
	v_mfma_f32_32x32x16_bf16 v[68:83], v[252:255], v[172:175], v[68:83]
	ds_read_b128 v[252:255], v243 offset:32
	s_waitcnt lgkmcnt(6)
; #define MFMA32(a, b, c) __builtin_amdgcn_mfma_f32_32x32x16_bf16((a), (b), (c), 0, 0, 0)
; DI void attn_unit(unsigned char* smem, const Params& P, int bh, int qb) {
;     ...
;     if (active) {
; #pragma unroll
;       for (int a = 0; a < 2; ++a)
; #pragma unroll
;         for (int i = 0; i < 16; ++i) S[a][i] = -sref;
;       __builtin_amdgcn_s_setprio(1);
; #pragma unroll
;       for (int ks = 0; ks < 12; ++ks) {
;         const bf16x8 a0 = *(const bf16x8*)(cK + l31 * KLD + ks * 16 + hh * 8), a1 = *(const bf16x8*)(cK + (32 + l31) * KLD + ks * 16 + hh * 8);
;         S[0] = MFMA32(a0, qf[ks], S[0]); S[1] = MFMA32(a1, qf[ks], S[1]);
;       }
;       __builtin_amdgcn_s_setprio(0);
;     }
;     { const bf16_t* vp_ = vtb + (size_t)(tid >> 3) * 8192 + jt * 64 + (tid & 7) * 8; vr0 = *(const uint4*)(vp_ + (size_t)0 * 8192); vr1 = *(const uint4*)(vp_ + (size_t)32 * 8192); vr2 = *(const uint4*)(vp_ + (size_t)64 * 8192); vr3 = *(const uint4*)(vp_ + (size_t)96 * 8192); }
;     __builtin_amdgcn_sched_barrier(0);
	v_mfma_f32_32x32x16_bf16 v[52:67], v[180:183], v[172:175], v[52:67]
	s_waitcnt lgkmcnt(5)
	v_mfma_f32_32x32x16_bf16 v[4:19], v[184:187], v[172:175], v[4:19]
	s_waitcnt lgkmcnt(2)
	v_mfma_f32_32x32x16_bf16 v[36:51], v[244:247], v[100:103], v[20:35]
	ds_read_b128 v[244:247], v243 offset:12864
	v_lshl_add_u64 v[180:181], s[10:11], 1, v[198:199]
	v_add_co_u32_e32 v176, vcc, s78, v180
	s_nop 1
	v_addc_co_u32_e32 v177, vcc, 0, v181, vcc
	s_waitcnt lgkmcnt(2)
	v_mfma_f32_32x32x16_bf16 v[20:35], v[248:251], v[100:103], v[20:35]
	ds_read_b128 v[248:251], v243 offset:96
	v_add_co_u32_e32 v182, vcc, 0x100000, v180
	global_load_dwordx4 v[172:175], v[180:181], off
	s_nop 0
	global_load_dwordx4 v[176:179], v[176:177], off
	s_waitcnt lgkmcnt(2)
	v_mfma_f32_32x32x16_bf16 v[36:51], v[252:255], v[104:107], v[36:51]
	ds_read_b128 v[252:255], v243 offset:12896
	v_addc_co_u32_e32 v183, vcc, 0, v181, vcc
	v_add_co_u32_e32 v180, vcc, 0x180000, v180
	s_nop 1
	v_addc_co_u32_e32 v181, vcc, 0, v181, vcc
	s_waitcnt lgkmcnt(7)
	v_mfma_f32_32x32x16_bf16 v[20:35], v[226:229], v[104:107], v[20:35]
	ds_read_b128 v[226:229], v243 offset:128
	global_load_dwordx4 v[184:187], v[182:183], off
	s_nop 0
	global_load_dwordx4 v[180:183], v[180:181], off
	s_waitcnt lgkmcnt(7)
	v_mfma_f32_32x32x16_bf16 v[36:51], v[230:233], v[108:111], v[36:51]
	ds_read_b128 v[230:233], v243 offset:12928
	s_waitcnt lgkmcnt(4)
	v_mfma_f32_32x32x16_bf16 v[20:35], v[244:247], v[108:111], v[20:35]
	ds_read_b128 v[244:247], v243 offset:160
	s_waitcnt lgkmcnt(4)
	v_mfma_f32_32x32x16_bf16 v[36:51], v[248:251], v[112:115], v[36:51]
	ds_read_b128 v[248:251], v243 offset:12960
	s_waitcnt lgkmcnt(4)
	v_mfma_f32_32x32x16_bf16 v[20:35], v[252:255], v[112:115], v[20:35]
	ds_read_b128 v[252:255], v243 offset:192
	s_waitcnt lgkmcnt(4)
	v_mfma_f32_32x32x16_bf16 v[36:51], v[226:229], v[116:119], v[36:51]
	ds_read_b128 v[226:229], v243 offset:12992
	s_waitcnt lgkmcnt(4)
	v_mfma_f32_32x32x16_bf16 v[20:35], v[230:233], v[116:119], v[20:35]
	ds_read_b128 v[230:233], v243 offset:224
	s_waitcnt lgkmcnt(4)
	v_mfma_f32_32x32x16_bf16 v[36:51], v[244:247], v[120:123], v[36:51]
	ds_read_b128 v[244:247], v243 offset:13024
	s_waitcnt lgkmcnt(4)
	v_mfma_f32_32x32x16_bf16 v[20:35], v[248:251], v[120:123], v[20:35]
	ds_read_b128 v[248:251], v243 offset:256
	s_waitcnt lgkmcnt(4)
	v_mfma_f32_32x32x16_bf16 v[36:51], v[252:255], v[124:127], v[36:51]
	ds_read_b128 v[252:255], v243 offset:13056
	s_waitcnt lgkmcnt(4)
	v_mfma_f32_32x32x16_bf16 v[20:35], v[226:229], v[124:127], v[20:35]
	ds_read_b128 v[226:229], v243 offset:288
	s_waitcnt lgkmcnt(4)
	v_mfma_f32_32x32x16_bf16 v[36:51], v[230:233], v[128:131], v[36:51]
	ds_read_b128 v[230:233], v243 offset:13088
	s_waitcnt lgkmcnt(4)
	v_mfma_f32_32x32x16_bf16 v[20:35], v[244:247], v[128:131], v[20:35]
	ds_read_b128 v[244:247], v243 offset:320
	s_waitcnt lgkmcnt(4)
	v_mfma_f32_32x32x16_bf16 v[36:51], v[248:251], v[132:135], v[36:51]
	ds_read_b128 v[248:251], v243 offset:13120
	s_waitcnt lgkmcnt(4)
	v_mfma_f32_32x32x16_bf16 v[20:35], v[252:255], v[132:135], v[20:35]
	ds_read_b128 v[252:255], v243 offset:352
	s_waitcnt lgkmcnt(4)
	v_mfma_f32_32x32x16_bf16 v[36:51], v[226:229], v[136:139], v[36:51]
	ds_read_b128 v[226:229], v243 offset:13152
	s_waitcnt lgkmcnt(4)
	v_mfma_f32_32x32x16_bf16 v[20:35], v[230:233], v[136:139], v[20:35]
	s_barrier
	s_waitcnt lgkmcnt(3)
	v_mfma_f32_32x32x16_bf16 v[36:51], v[244:247], v[140:143], v[36:51]
	s_waitcnt lgkmcnt(2)
	v_mfma_f32_32x32x16_bf16 v[20:35], v[248:251], v[140:143], v[20:35]
	s_waitcnt lgkmcnt(1)
	v_mfma_f32_32x32x16_bf16 v[36:51], v[252:255], v[144:147], v[36:51]
	s_waitcnt lgkmcnt(0)
	v_mfma_f32_32x32x16_bf16 v[20:35], v[226:229], v[144:147], v[20:35]
	s_nop 11
	s_setprio 0
	s_branch .Lafter_ba_2

; DI int crow(int i, int h) { return (i & 3) + 8 * (i >> 2) + 4 * h; }
; DI void attn_unit(unsigned char* smem, const Params& P, int bh, int qb) {
;     ...
;       if (jt >= ntiles - 2) {
; #pragma unroll
;         for (int kt = 0; kt < 2; ++kt)
; #pragma unroll
;           for (int i = 0; i < 16; ++i) { const int key = jt * 64 + kt * 32 + crow(i, hh); if (key > qrow) S[kt][i] = -1e30f; }
;       }
.Lafter_ba_2:
	s_and_saveexec_b64 s[16:17], s[2:3]
	s_cbranch_execz .LBB0_1417
	s_cmp_lt_u32 s22, s13
	s_cbranch_scc1 .LBB0_1414
	v_add_u32_e32 v225, s21, v219
	v_add_u32_e32 v226, 64, v225
	v_cmp_le_i32_e32 vcc, v226, v188
	s_nop 1
	v_cndmask_b32_e32 v36, v213, v36, vcc
	v_cmp_lt_i32_e32 vcc, v226, v188
	v_add_u32_e32 v226, 0x42, v225
	s_nop 0
	v_cndmask_b32_e32 v37, v213, v37, vcc
	v_cmp_le_i32_e32 vcc, v226, v188
	v_add_u32_e32 v226, 0x43, v225
	s_nop 0
	v_cndmask_b32_e32 v38, v213, v38, vcc
	v_cmp_le_i32_e32 vcc, v226, v188
	v_add_u32_e32 v226, 0x48, v225
	s_nop 0
	v_cndmask_b32_e32 v39, v213, v39, vcc
	v_cmp_le_i32_e32 vcc, v226, v188
	v_add_u32_e32 v226, 0x49, v225
	s_nop 0
	v_cndmask_b32_e32 v40, v213, v40, vcc
	v_cmp_le_i32_e32 vcc, v226, v188
	v_add_u32_e32 v226, 0x4a, v225
	s_nop 0
	v_cndmask_b32_e32 v41, v213, v41, vcc
	v_cmp_le_i32_e32 vcc, v226, v188
	v_add_u32_e32 v226, 0x4b, v225
	s_nop 0
	v_cndmask_b32_e32 v42, v213, v42, vcc
	v_cmp_le_i32_e32 vcc, v226, v188
	v_add_u32_e32 v226, 0x50, v225
	s_nop 0
	v_cndmask_b32_e32 v43, v213, v43, vcc
	v_cmp_le_i32_e32 vcc, v226, v188
	v_add_u32_e32 v226, 0x51, v225
	s_nop 0
	v_cndmask_b32_e32 v44, v213, v44, vcc
	v_cmp_le_i32_e32 vcc, v226, v188
	v_add_u32_e32 v226, 0x52, v225
	s_nop 0
	v_cndmask_b32_e32 v45, v213, v45, vcc
	v_cmp_le_i32_e32 vcc, v226, v188
	v_add_u32_e32 v226, 0x53, v225
	s_nop 0
	v_cndmask_b32_e32 v46, v213, v46, vcc
	v_cmp_le_i32_e32 vcc, v226, v188
	v_add_u32_e32 v226, 0x58, v225
	s_nop 0
	v_cndmask_b32_e32 v47, v213, v47, vcc
	v_cmp_le_i32_e32 vcc, v226, v188
	v_add_u32_e32 v226, 0x59, v225
	s_nop 0
	v_cndmask_b32_e32 v48, v213, v48, vcc
	v_cmp_le_i32_e32 vcc, v226, v188
	v_add_u32_e32 v226, 0x5a, v225
	s_nop 0
	v_cndmask_b32_e32 v49, v213, v49, vcc
	v_cmp_le_i32_e32 vcc, v226, v188
	v_add_u32_e32 v226, 0x5b, v225
	s_nop 0
	v_cndmask_b32_e32 v50, v213, v50, vcc
	v_cmp_le_i32_e32 vcc, v226, v188
	v_add_u32_e32 v226, 0x60, v225
	s_nop 0
	v_cndmask_b32_e32 v51, v213, v51, vcc
	v_cmp_le_i32_e32 vcc, v226, v188
	v_add_u32_e32 v226, 0x61, v225
	s_nop 0
	v_cndmask_b32_e32 v20, v213, v20, vcc
	v_cmp_le_i32_e32 vcc, v226, v188
	v_add_u32_e32 v226, 0x62, v225
	s_nop 0
	v_cndmask_b32_e32 v21, v213, v21, vcc
	v_cmp_le_i32_e32 vcc, v226, v188
	v_add_u32_e32 v226, 0x63, v225
	s_nop 0
	v_cndmask_b32_e32 v22, v213, v22, vcc
	v_cmp_le_i32_e32 vcc, v226, v188
	v_add_u32_e32 v226, 0x68, v225
	s_nop 0
	v_cndmask_b32_e32 v23, v213, v23, vcc
	v_cmp_le_i32_e32 vcc, v226, v188
	v_add_u32_e32 v226, 0x69, v225
	s_nop 0
	v_cndmask_b32_e32 v24, v213, v24, vcc
	v_cmp_le_i32_e32 vcc, v226, v188
	v_add_u32_e32 v226, 0x6a, v225
	s_nop 0
	v_cndmask_b32_e32 v25, v213, v25, vcc
	v_cmp_le_i32_e32 vcc, v226, v188
	v_add_u32_e32 v226, 0x6b, v225
	s_nop 0
	v_cndmask_b32_e32 v26, v213, v26, vcc
	v_cmp_le_i32_e32 vcc, v226, v188
	v_add_u32_e32 v226, 0x70, v225
	s_nop 0
	v_cndmask_b32_e32 v27, v213, v27, vcc
	v_cmp_le_i32_e32 vcc, v226, v188
	v_add_u32_e32 v226, 0x71, v225
	s_nop 0
	v_cndmask_b32_e32 v28, v213, v28, vcc
	v_cmp_le_i32_e32 vcc, v226, v188
	v_add_u32_e32 v226, 0x72, v225
	s_nop 0
	v_cndmask_b32_e32 v29, v213, v29, vcc
	v_cmp_le_i32_e32 vcc, v226, v188
	v_add_u32_e32 v226, 0x73, v225
	s_nop 0
	v_cndmask_b32_e32 v30, v213, v30, vcc
	v_cmp_le_i32_e32 vcc, v226, v188
	v_add_u32_e32 v226, 0x78, v225
	s_nop 0
	v_cndmask_b32_e32 v31, v213, v31, vcc
	v_cmp_le_i32_e32 vcc, v226, v188
	v_add_u32_e32 v226, 0x79, v225
	s_nop 0
	v_cndmask_b32_e32 v32, v213, v32, vcc
	v_cmp_le_i32_e32 vcc, v226, v188
	v_add_u32_e32 v226, 0x7a, v225
	v_add_u32_e32 v225, 0x7b, v225
	v_cndmask_b32_e32 v33, v213, v33, vcc
	v_cmp_le_i32_e32 vcc, v226, v188
	s_nop 1
	v_cndmask_b32_e32 v34, v213, v34, vcc
	v_cmp_le_i32_e32 vcc, v225, v188
	s_nop 1
	v_cndmask_b32_e32 v35, v213, v35, vcc
